# K=2816 sample-row mini GEMMs: third k-pair's loads issued up front (three pairs in flight at the start)
# baseline (speedup 1.0000x reference)
.LBB0_121:
	v_and_b32_e32 v129, 63, v1
	v_lshrrev_b32_e32 v130, 3, v129
	v_readlane_b32 s17, v253, 12
	s_mul_i32 s16, s20, 0x2d00
	s_add_i32 s16, s16, 0
	v_or_b32_e32 v52, s17, v130
	v_readlane_b32 s17, v253, 6
	s_add_i32 s24, s16, 0x10000
	s_lshl_b32 s16, s18, 6
	v_or_b32_e32 v54, s17, v130
	v_readlane_b32 s17, v253, 7
	v_or_b32_e32 v2, s74, v130
	v_mul_u32_u24_e32 v2, 0xb00, v2
	v_or_b32_e32 v60, s17, v130
	v_readlane_b32 s17, v253, 8
	v_lshlrev_b32_e32 v44, 1, v2
	v_lshlrev_b32_e32 v2, 4, v129
	v_or_b32_e32 v62, s17, v130
	v_readlane_b32 s17, v253, 9
	v_and_b32_e32 v2, 0x70, v2
	s_movk_i32 s26, 0x1600
	v_or_b32_e32 v68, s17, v130
	v_readlane_b32 s17, v253, 10
	v_lshl_add_u64 v[46:47], s[44:45], 0, v[2:3]
	v_lshl_add_u64 v[88:89], s[46:47], 0, v[2:3]
	v_or_b32_e32 v70, s17, v130
	v_readlane_b32 s17, v253, 11
	v_add_u32_e32 v131, s24, v2
	v_mov_b32_e32 v45, v3
	v_or_b32_e32 v76, s17, v130
	v_readlane_b32 s17, v253, 13
	s_mov_b32 s25, 0xb000
	v_mad_u32_u24 v160, v130, s94, v131
	v_or_b32_e32 v120, s17, v130
	s_ashr_i32 s17, s16, 31
	s_lshl_b64 s[16:17], s[16:17], 1
	s_add_u32 s18, s16, 0x80
	s_addc_u32 s19, s17, 0
	s_add_u32 s22, s46, s16
	s_addc_u32 s23, s47, s17
	v_lshl_add_u64 v[40:41], s[22:23], 0, v[2:3]
	v_mad_i64_i32 v[104:105], s[22:23], v76, s26, v[40:41]
	v_mad_i64_i32 v[106:107], s[22:23], v70, s26, v[40:41]
	v_mad_i64_i32 v[108:109], s[22:23], v68, s26, v[40:41]
	v_mad_i64_i32 v[110:111], s[22:23], v62, s26, v[40:41]
	v_mad_i64_i32 v[112:113], s[22:23], v60, s26, v[40:41]
	v_mad_i64_i32 v[114:115], s[22:23], v54, s26, v[40:41]
	v_mad_i64_i32 v[116:117], s[22:23], v52, s26, v[40:41]
	s_add_u32 s22, s44, s16
	s_addc_u32 s23, s45, s17
	v_lshl_add_u64 v[8:9], s[22:23], 0, v[2:3]
	v_add_u32_e32 v2, 0xb000, v44
	v_lshl_add_u64 v[4:5], v[8:9], 0, v[2:3]
	global_load_dwordx4 v[4:7], v[4:5], off
	v_lshl_add_u64 v[118:119], v[8:9], 0, v[44:45]
	global_load_dwordx4 v[8:11], v[116:117], off
	global_load_dwordx4 v[12:15], v[118:119], off
	global_load_dwordx4 v[16:19], v[112:113], off
	global_load_dwordx4 v[20:23], v[114:115], off
	global_load_dwordx4 v[24:27], v[108:109], off
	global_load_dwordx4 v[28:31], v[110:111], off
	global_load_dwordx4 v[32:35], v[104:105], off
	global_load_dwordx4 v[36:39], v[106:107], off
	v_mad_i64_i32 v[40:41], s[22:23], v120, s26, v[40:41]
	global_load_dwordx4 v[40:43], v[40:41], off
	v_lshl_add_u64 v[44:45], v[46:47], 0, v[44:45]
	v_lshl_add_u64 v[44:45], v[44:45], 0, s[18:19]
	v_add_co_u32_e32 v48, vcc, s25, v44
	v_mad_i64_i32 v[52:53], s[22:23], v52, s26, v[88:89]
	v_mad_i64_i32 v[54:55], s[22:23], v54, s26, v[88:89]
	v_mad_i64_i32 v[60:61], s[22:23], v60, s26, v[88:89]
	v_mad_i64_i32 v[62:63], s[22:23], v62, s26, v[88:89]
	v_mad_i64_i32 v[68:69], s[22:23], v68, s26, v[88:89]
	v_mad_i64_i32 v[70:71], s[22:23], v70, s26, v[88:89]
	v_mad_i64_i32 v[76:77], s[22:23], v76, s26, v[88:89]
	v_mad_i64_i32 v[78:79], s[22:23], v120, s26, v[88:89]
	v_addc_co_u32_e32 v49, vcc, 0, v45, vcc
	v_lshl_add_u64 v[52:53], v[52:53], 0, s[18:19]
	v_lshl_add_u64 v[56:57], v[54:55], 0, s[18:19]
	v_lshl_add_u64 v[60:61], v[60:61], 0, s[18:19]
	v_lshl_add_u64 v[64:65], v[62:63], 0, s[18:19]
	v_lshl_add_u64 v[68:69], v[68:69], 0, s[18:19]
	v_lshl_add_u64 v[72:73], v[70:71], 0, s[18:19]
	v_lshl_add_u64 v[76:77], v[76:77], 0, s[18:19]
	v_lshl_add_u64 v[80:81], v[78:79], 0, s[18:19]
	global_load_dwordx4 v[44:47], v[44:45], off
	s_nop 0
	global_load_dwordx4 v[48:51], v[48:49], off
	s_nop 0
	global_load_dwordx4 v[52:55], v[52:53], off
	s_nop 0
	global_load_dwordx4 v[56:59], v[56:57], off
	s_nop 0
	global_load_dwordx4 v[60:63], v[60:61], off
	s_nop 0
	global_load_dwordx4 v[64:67], v[64:65], off
	s_nop 0
	global_load_dwordx4 v[68:71], v[68:69], off
	s_nop 0
	global_load_dwordx4 v[72:75], v[72:73], off
	s_nop 0
	global_load_dwordx4 v[76:79], v[76:77], off
	s_nop 0
	global_load_dwordx4 v[80:83], v[80:81], off
	v_add_co_u32_e32 v158, vcc, s25, v118
	v_addc_co_u32_e32 v159, vcc, 0, v119, vcc
	global_load_dwordx4 v[84:87], v[158:159], off offset:256
	v_lshl_add_u64 v[164:165], v[88:89], 0, s[16:17]
	global_load_dwordx4 v[88:91], v[118:119], off offset:256
	global_load_dwordx4 v[92:95], v[116:117], off offset:256
	global_load_dwordx4 v[96:99], v[114:115], off offset:256
	global_load_dwordx4 v[134:137], v[112:113], off offset:256
	global_load_dwordx4 v[138:141], v[110:111], off offset:256
	global_load_dwordx4 v[142:145], v[108:109], off offset:256
	global_load_dwordx4 v[146:149], v[106:107], off offset:256
	global_load_dwordx4 v[150:153], v[104:105], off offset:256
	v_mad_i64_i32 v[120:121], s[16:17], v120, s26, v[164:165]
	global_load_dwordx4 v[154:157], v[120:121], off offset:256
	v_mul_u32_u24_e32 v132, 0x90, v127
	v_and_b32_e32 v162, 48, v1
	s_waitcnt vmcnt(27)
	ds_write_b128 v160, v[12:15]
	ds_write_b128 v160, v[4:7] offset:1152
	ds_write_b128 v160, v[8:11] offset:2304
	s_waitcnt vmcnt(25)
	ds_write_b128 v160, v[20:23] offset:3456
	ds_write_b128 v160, v[16:19] offset:4608
	s_waitcnt vmcnt(23)
	ds_write_b128 v160, v[28:31] offset:5760
	ds_write_b128 v160, v[24:27] offset:6912
	s_waitcnt vmcnt(21)
	ds_write_b128 v160, v[36:39] offset:8064
	ds_write_b128 v160, v[32:35] offset:9216
	s_waitcnt vmcnt(20)
	ds_write_b128 v160, v[40:43] offset:10368
	v_add3_u32 v2, s24, v132, v162
	ds_read_b128 v[4:7], v2
	v_add_u32_e32 v133, s24, v162
	v_mad_u32_u24 v161, v127, s94, v133
	ds_read_b128 v[8:11], v161 offset:2304
	ds_read_b128 v[12:15], v161 offset:4608
	ds_read_b128 v[16:19], v161 offset:6912
	ds_read_b128 v[20:23], v161 offset:9216
	ds_read_b128 v[24:27], v2 offset:64
	s_waitcnt lgkmcnt(4)
	v_mfma_f32_16x16x32_bf16 v[8:11], v[4:7], v[8:11], 0
	s_waitcnt lgkmcnt(3)
	v_mfma_f32_16x16x32_bf16 v[12:15], v[4:7], v[12:15], 0
	s_andn2_b64 vcc, exec, s[14:15]
	s_waitcnt lgkmcnt(2)
	v_mfma_f32_16x16x32_bf16 v[16:19], v[4:7], v[16:19], 0
	s_waitcnt lgkmcnt(1)
	v_mfma_f32_16x16x32_bf16 v[4:7], v[4:7], v[20:23], 0
	ds_read_b128 v[20:23], v161 offset:2368
	ds_read_b128 v[28:31], v161 offset:4672
	s_waitcnt lgkmcnt(1)
	v_mfma_f32_16x16x32_bf16 v[8:11], v[24:27], v[20:23], v[8:11]
	ds_read_b128 v[20:23], v161 offset:6976
	ds_read_b128 v[32:35], v161 offset:9280
	s_waitcnt lgkmcnt(2)
	v_mfma_f32_16x16x32_bf16 v[12:15], v[24:27], v[28:31], v[12:15]
	s_waitcnt vmcnt(19)
	ds_write_b128 v160, v[44:47]
	s_waitcnt vmcnt(18)
	ds_write_b128 v160, v[48:51] offset:1152
	s_waitcnt vmcnt(17)
	ds_write_b128 v160, v[52:55] offset:2304
	s_waitcnt vmcnt(16)
	ds_write_b128 v160, v[56:59] offset:3456
	s_waitcnt vmcnt(15)
	ds_write_b128 v160, v[60:63] offset:4608
	s_waitcnt vmcnt(14)
	ds_write_b128 v160, v[64:67] offset:5760
	s_waitcnt vmcnt(13)
	ds_write_b128 v160, v[68:71] offset:6912
	s_waitcnt vmcnt(12)
	ds_write_b128 v160, v[72:75] offset:8064
	s_waitcnt vmcnt(11)
	ds_write_b128 v160, v[76:79] offset:9216
	s_waitcnt vmcnt(10)
	ds_write_b128 v160, v[80:83] offset:10368
	s_waitcnt lgkmcnt(11)
	v_mfma_f32_16x16x32_bf16 v[16:19], v[24:27], v[20:23], v[16:19]
	ds_read_b128 v[20:23], v2
	s_waitcnt lgkmcnt(11)
	v_mfma_f32_16x16x32_bf16 v[4:7], v[24:27], v[32:35], v[4:7]
	ds_read_b128 v[24:27], v161 offset:2304
	s_waitcnt lgkmcnt(0)
	v_mfma_f32_16x16x32_bf16 v[8:11], v[20:23], v[24:27], v[8:11]
	ds_read_b128 v[24:27], v161 offset:4608
	s_waitcnt lgkmcnt(0)
	v_mfma_f32_16x16x32_bf16 v[12:15], v[20:23], v[24:27], v[12:15]
	ds_read_b128 v[24:27], v161 offset:6912
	ds_read_b128 v[28:31], v161 offset:9216
	ds_read_b128 v[44:47], v2 offset:64
	s_waitcnt lgkmcnt(1)
	v_mfma_f32_16x16x32_bf16 v[48:51], v[20:23], v[28:31], v[4:7]
	s_nop 2
	ds_read_b128 v[4:7], v161 offset:2368
	s_waitcnt lgkmcnt(0)
	v_mfma_f32_16x16x32_bf16 v[52:55], v[44:47], v[4:7], v[8:11]
	ds_read_b128 v[4:7], v161 offset:4672
	v_mfma_f32_16x16x32_bf16 v[16:19], v[20:23], v[24:27], v[16:19]
	s_waitcnt lgkmcnt(0)
	v_mfma_f32_16x16x32_bf16 v[56:59], v[44:47], v[4:7], v[12:15]
	ds_read_b128 v[4:7], v161 offset:6976
	ds_read_b128 v[60:63], v161 offset:9280
	s_waitcnt lgkmcnt(1)
	v_mfma_f32_16x16x32_bf16 v[64:67], v[44:47], v[4:7], v[16:19]
	global_load_dwordx4 v[4:7], v[118:119], off offset:384
	global_load_dwordx4 v[8:11], v[116:117], off offset:384
	global_load_dwordx4 v[12:15], v[114:115], off offset:384
	global_load_dwordx4 v[16:19], v[112:113], off offset:384
	global_load_dwordx4 v[20:23], v[110:111], off offset:384
	global_load_dwordx4 v[36:39], v[158:159], off offset:384
	global_load_dwordx4 v[24:27], v[108:109], off offset:384
	global_load_dwordx4 v[28:31], v[106:107], off offset:384
	global_load_dwordx4 v[32:35], v[104:105], off offset:384
	global_load_dwordx4 v[40:43], v[120:121], off offset:384
	s_waitcnt vmcnt(18)
	ds_write_b128 v160, v[88:91]
	ds_write_b128 v160, v[84:87] offset:1152
	s_waitcnt vmcnt(17)
	ds_write_b128 v160, v[92:95] offset:2304
	s_waitcnt vmcnt(16)
	ds_write_b128 v160, v[96:99] offset:3456
	s_waitcnt vmcnt(15)
	ds_write_b128 v160, v[134:137] offset:4608
	s_waitcnt vmcnt(14)
	ds_write_b128 v160, v[138:141] offset:5760
	s_waitcnt vmcnt(13)
	ds_write_b128 v160, v[142:145] offset:6912
	s_waitcnt vmcnt(12)
	ds_write_b128 v160, v[146:149] offset:8064
	s_waitcnt vmcnt(11)
	ds_write_b128 v160, v[150:153] offset:9216
	s_waitcnt vmcnt(10)
	ds_write_b128 v160, v[154:157] offset:10368
	ds_read_b128 v[68:71], v2
	s_waitcnt lgkmcnt(11)
	v_mfma_f32_16x16x32_bf16 v[44:47], v[44:47], v[60:63], v[48:51]
	s_nop 2
	ds_read_b128 v[48:51], v161 offset:2304
	s_waitcnt lgkmcnt(0)
	v_mfma_f32_16x16x32_bf16 v[48:51], v[68:71], v[48:51], v[52:55]
	s_nop 2
	ds_read_b128 v[52:55], v161 offset:4608
	s_waitcnt lgkmcnt(0)
	v_mfma_f32_16x16x32_bf16 v[52:55], v[68:71], v[52:55], v[56:59]
	s_nop 2
	ds_read_b128 v[56:59], v161 offset:6912
	ds_read_b128 v[60:63], v161 offset:9216
	ds_read_b128 v[88:91], v2 offset:64
	s_waitcnt lgkmcnt(2)
	v_mfma_f32_16x16x32_bf16 v[84:87], v[68:71], v[56:59], v[64:67]
	s_waitcnt lgkmcnt(1)
	v_mfma_f32_16x16x32_bf16 v[92:95], v[68:71], v[60:63], v[44:47]
	s_nop 2
	ds_read_b128 v[44:47], v161 offset:2368
	ds_read_b128 v[56:59], v161 offset:4672
	ds_read_b128 v[134:137], v161 offset:6976
	ds_read_b128 v[138:141], v161 offset:9280
	s_waitcnt lgkmcnt(3)
	v_mfma_f32_16x16x32_bf16 v[96:99], v[88:91], v[44:47], v[48:51]
	s_waitcnt lgkmcnt(2)
	v_mfma_f32_16x16x32_bf16 v[142:145], v[88:91], v[56:59], v[52:55]
	global_load_dwordx4 v[44:47], v[118:119], off offset:512
	global_load_dwordx4 v[48:51], v[116:117], off offset:512
	s_nop 0
	global_load_dwordx4 v[52:55], v[114:115], off offset:512
	global_load_dwordx4 v[56:59], v[112:113], off offset:512
	global_load_dwordx4 v[60:63], v[110:111], off offset:512
	global_load_dwordx4 v[64:67], v[108:109], off offset:512
	global_load_dwordx4 v[68:71], v[106:107], off offset:512
	global_load_dwordx4 v[72:75], v[104:105], off offset:512
	global_load_dwordx4 v[80:83], v[158:159], off offset:512
	global_load_dwordx4 v[76:79], v[120:121], off offset:512
	s_waitcnt vmcnt(19)
	ds_write_b128 v160, v[4:7]
	s_waitcnt vmcnt(14)
	ds_write_b128 v160, v[36:39] offset:1152
	ds_write_b128 v160, v[8:11] offset:2304
	ds_write_b128 v160, v[12:15] offset:3456
	ds_write_b128 v160, v[16:19] offset:4608
	ds_write_b128 v160, v[20:23] offset:5760
	s_waitcnt vmcnt(13)
	ds_write_b128 v160, v[24:27] offset:6912
	s_waitcnt vmcnt(12)
	ds_write_b128 v160, v[28:31] offset:8064
	s_waitcnt vmcnt(11)
	ds_write_b128 v160, v[32:35] offset:9216
	s_waitcnt vmcnt(10)
	ds_write_b128 v160, v[40:43] offset:10368
	s_waitcnt lgkmcnt(11)
	v_mfma_f32_16x16x32_bf16 v[84:87], v[88:91], v[134:137], v[84:87]
	ds_read_b128 v[134:137], v2
	s_waitcnt lgkmcnt(11)
	v_mfma_f32_16x16x32_bf16 v[88:91], v[88:91], v[138:141], v[92:95]
	s_nop 2
	ds_read_b128 v[92:95], v161 offset:2304
	s_waitcnt lgkmcnt(0)
	v_mfma_f32_16x16x32_bf16 v[92:95], v[134:137], v[92:95], v[96:99]
	s_nop 2
	ds_read_b128 v[96:99], v161 offset:4608
	s_waitcnt lgkmcnt(0)
	v_mfma_f32_16x16x32_bf16 v[96:99], v[134:137], v[96:99], v[142:145]
	ds_read_b128 v[138:141], v161 offset:6912
	s_nop 1
	ds_read_b128 v[142:145], v161 offset:9216
	ds_read_b128 v[146:149], v2 offset:64
	s_waitcnt lgkmcnt(2)
	v_mfma_f32_16x16x32_bf16 v[138:141], v[134:137], v[138:141], v[84:87]
	s_nop 2
	ds_read_b128 v[84:87], v161 offset:2368
	s_waitcnt lgkmcnt(2)
	v_mfma_f32_16x16x32_bf16 v[134:137], v[134:137], v[142:145], v[88:91]
	s_nop 2
	ds_read_b128 v[88:91], v161 offset:4672
	s_waitcnt lgkmcnt(1)
	v_mfma_f32_16x16x32_bf16 v[84:87], v[146:149], v[84:87], v[92:95]
	s_nop 2
	ds_read_b128 v[92:95], v161 offset:6976
	ds_read_b128 v[142:145], v161 offset:9280
	s_waitcnt lgkmcnt(2)
	v_mfma_f32_16x16x32_bf16 v[88:91], v[146:149], v[88:91], v[96:99]
	s_waitcnt lgkmcnt(1)
	v_mfma_f32_16x16x32_bf16 v[96:99], v[146:149], v[92:95], v[138:141]
	v_cndmask_b32_e64 v92, 0, 1, s[14:15]
	v_cmp_ne_u32_e64 s[38:39], 1, v92
	s_waitcnt lgkmcnt(0)
	v_mfma_f32_16x16x32_bf16 v[92:95], v[146:149], v[142:145], v[134:137]
	s_cbranch_vccnz .LBB0_123
	v_add_co_u32_e32 v36, vcc, 0xb000, v118
	s_nop 1
	v_addc_co_u32_e32 v37, vcc, 0, v119, vcc
	global_load_dwordx4 v[4:7], v[118:119], off offset:640
	global_load_dwordx4 v[8:11], v[116:117], off offset:640
	global_load_dwordx4 v[12:15], v[114:115], off offset:640
	global_load_dwordx4 v[16:19], v[112:113], off offset:640
	global_load_dwordx4 v[20:23], v[110:111], off offset:640
	global_load_dwordx4 v[24:27], v[108:109], off offset:640
	global_load_dwordx4 v[28:31], v[106:107], off offset:640
	global_load_dwordx4 v[32:35], v[104:105], off offset:640
	s_nop 0
	global_load_dwordx4 v[36:39], v[36:37], off offset:640
	s_nop 0
	global_load_dwordx4 v[40:43], v[120:121], off offset:640

.LBB0_194:
	v_and_b32_e32 v129, 63, v123
	v_lshrrev_b32_e32 v130, 3, v129
	v_readlane_b32 s17, v253, 12
	s_mul_i32 s16, s20, 0x2d00
	s_add_i32 s16, s16, 0
	v_or_b32_e32 v52, s17, v130
	v_readlane_b32 s17, v253, 6
	s_add_i32 s21, s16, 0x10000
	s_lshl_b32 s16, s18, 6
	v_or_b32_e32 v54, s17, v130
	v_readlane_b32 s17, v253, 7
	v_or_b32_e32 v2, s74, v130
	v_mul_u32_u24_e32 v2, 0xb00, v2
	v_or_b32_e32 v60, s17, v130
	v_readlane_b32 s17, v253, 8
	v_lshlrev_b32_e32 v44, 1, v2
	v_lshlrev_b32_e32 v2, 4, v129
	v_or_b32_e32 v62, s17, v130
	v_readlane_b32 s17, v253, 9
	v_and_b32_e32 v2, 0x70, v2
	s_movk_i32 s26, 0x1600
	v_or_b32_e32 v68, s17, v130
	v_readlane_b32 s17, v253, 10
	v_lshl_add_u64 v[46:47], s[44:45], 0, v[2:3]
	v_lshl_add_u64 v[88:89], s[46:47], 0, v[2:3]
	v_or_b32_e32 v70, s17, v130
	v_readlane_b32 s17, v253, 11
	v_add_u32_e32 v131, s21, v2
	v_mov_b32_e32 v45, v3
	v_or_b32_e32 v76, s17, v130
	v_readlane_b32 s17, v253, 13
	s_mov_b32 s23, 0xb000
	v_mad_u32_u24 v160, v130, s94, v131
	v_or_b32_e32 v118, s17, v130
	s_ashr_i32 s17, s16, 31
	s_lshl_b64 s[16:17], s[16:17], 1
	s_add_u32 s18, s16, 0x80
	s_addc_u32 s19, s17, 0
	s_add_u32 s24, s46, s16
	s_addc_u32 s25, s47, s17
	v_lshl_add_u64 v[40:41], s[24:25], 0, v[2:3]
	v_mad_i64_i32 v[102:103], s[24:25], v76, s26, v[40:41]
	v_mad_i64_i32 v[104:105], s[24:25], v70, s26, v[40:41]
	v_mad_i64_i32 v[106:107], s[24:25], v68, s26, v[40:41]
	v_mad_i64_i32 v[108:109], s[24:25], v62, s26, v[40:41]
	v_mad_i64_i32 v[110:111], s[24:25], v60, s26, v[40:41]
	v_mad_i64_i32 v[112:113], s[24:25], v54, s26, v[40:41]
	v_mad_i64_i32 v[114:115], s[24:25], v52, s26, v[40:41]
	s_add_u32 s24, s44, s16
	s_addc_u32 s25, s45, s17
	v_lshl_add_u64 v[8:9], s[24:25], 0, v[2:3]
	v_add_u32_e32 v2, 0xb000, v44
	v_lshl_add_u64 v[4:5], v[8:9], 0, v[2:3]
	global_load_dwordx4 v[4:7], v[4:5], off
	v_lshl_add_u64 v[116:117], v[8:9], 0, v[44:45]
	global_load_dwordx4 v[8:11], v[114:115], off
	global_load_dwordx4 v[12:15], v[116:117], off
	global_load_dwordx4 v[16:19], v[110:111], off
	global_load_dwordx4 v[20:23], v[112:113], off
	global_load_dwordx4 v[24:27], v[106:107], off
	global_load_dwordx4 v[28:31], v[108:109], off
	global_load_dwordx4 v[32:35], v[102:103], off
	global_load_dwordx4 v[36:39], v[104:105], off
	v_mad_i64_i32 v[40:41], s[24:25], v118, s26, v[40:41]
	global_load_dwordx4 v[40:43], v[40:41], off
	v_lshl_add_u64 v[44:45], v[46:47], 0, v[44:45]
	v_lshl_add_u64 v[44:45], v[44:45], 0, s[18:19]
	v_add_co_u32_e32 v48, vcc, s23, v44
	v_mad_i64_i32 v[52:53], s[24:25], v52, s26, v[88:89]
	v_mad_i64_i32 v[54:55], s[24:25], v54, s26, v[88:89]
	v_mad_i64_i32 v[60:61], s[24:25], v60, s26, v[88:89]
	v_mad_i64_i32 v[62:63], s[24:25], v62, s26, v[88:89]
	v_mad_i64_i32 v[68:69], s[24:25], v68, s26, v[88:89]
	v_mad_i64_i32 v[70:71], s[24:25], v70, s26, v[88:89]
	v_mad_i64_i32 v[76:77], s[24:25], v76, s26, v[88:89]
	v_mad_i64_i32 v[78:79], s[24:25], v118, s26, v[88:89]
	v_addc_co_u32_e32 v49, vcc, 0, v45, vcc
	v_lshl_add_u64 v[52:53], v[52:53], 0, s[18:19]
	v_lshl_add_u64 v[56:57], v[54:55], 0, s[18:19]
	v_lshl_add_u64 v[60:61], v[60:61], 0, s[18:19]
	v_lshl_add_u64 v[64:65], v[62:63], 0, s[18:19]
	v_lshl_add_u64 v[68:69], v[68:69], 0, s[18:19]
	v_lshl_add_u64 v[72:73], v[70:71], 0, s[18:19]
	v_lshl_add_u64 v[76:77], v[76:77], 0, s[18:19]
	v_lshl_add_u64 v[80:81], v[78:79], 0, s[18:19]
	global_load_dwordx4 v[44:47], v[44:45], off
	s_nop 0
	global_load_dwordx4 v[48:51], v[48:49], off
	s_nop 0
	global_load_dwordx4 v[52:55], v[52:53], off
	s_nop 0
	global_load_dwordx4 v[56:59], v[56:57], off
	s_nop 0
	global_load_dwordx4 v[60:63], v[60:61], off
	s_nop 0
	global_load_dwordx4 v[64:67], v[64:65], off
	s_nop 0
	global_load_dwordx4 v[68:71], v[68:69], off
	s_nop 0
	global_load_dwordx4 v[72:75], v[72:73], off
	s_nop 0
	global_load_dwordx4 v[76:79], v[76:77], off
	s_nop 0
	global_load_dwordx4 v[80:83], v[80:81], off
	v_add_co_u32_e32 v158, vcc, s23, v116
	v_addc_co_u32_e32 v159, vcc, 0, v117, vcc
	global_load_dwordx4 v[84:87], v[158:159], off offset:256
	v_lshl_add_u64 v[164:165], v[88:89], 0, s[16:17]
	global_load_dwordx4 v[88:91], v[116:117], off offset:256
	global_load_dwordx4 v[92:95], v[114:115], off offset:256
	global_load_dwordx4 v[96:99], v[112:113], off offset:256
	global_load_dwordx4 v[134:137], v[110:111], off offset:256
	global_load_dwordx4 v[138:141], v[108:109], off offset:256
	global_load_dwordx4 v[142:145], v[106:107], off offset:256
	global_load_dwordx4 v[146:149], v[104:105], off offset:256
	global_load_dwordx4 v[150:153], v[102:103], off offset:256
	v_mad_i64_i32 v[118:119], s[16:17], v118, s26, v[164:165]
	global_load_dwordx4 v[154:157], v[118:119], off offset:256
	v_mul_u32_u24_e32 v132, 0x90, v126
	v_and_b32_e32 v162, 48, v123
	s_waitcnt vmcnt(27)
	ds_write_b128 v160, v[12:15]
	ds_write_b128 v160, v[4:7] offset:1152
	ds_write_b128 v160, v[8:11] offset:2304
	s_waitcnt vmcnt(25)
	ds_write_b128 v160, v[20:23] offset:3456
	ds_write_b128 v160, v[16:19] offset:4608
	s_waitcnt vmcnt(23)
	ds_write_b128 v160, v[28:31] offset:5760
	ds_write_b128 v160, v[24:27] offset:6912
	s_waitcnt vmcnt(21)
	ds_write_b128 v160, v[36:39] offset:8064
	ds_write_b128 v160, v[32:35] offset:9216
	s_waitcnt vmcnt(20)
	ds_write_b128 v160, v[40:43] offset:10368
	v_add3_u32 v2, s21, v132, v162
	ds_read_b128 v[4:7], v2
	v_add_u32_e32 v133, s21, v162
	v_mad_u32_u24 v161, v126, s94, v133
	ds_read_b128 v[8:11], v161 offset:2304
	ds_read_b128 v[12:15], v161 offset:4608
	ds_read_b128 v[16:19], v161 offset:6912
	ds_read_b128 v[20:23], v161 offset:9216
	ds_read_b128 v[24:27], v2 offset:64
	s_waitcnt lgkmcnt(4)
	v_mfma_f32_16x16x32_bf16 v[8:11], v[4:7], v[8:11], 0
	s_waitcnt lgkmcnt(3)
	v_mfma_f32_16x16x32_bf16 v[12:15], v[4:7], v[12:15], 0
	s_andn2_b64 vcc, exec, s[14:15]
	s_waitcnt lgkmcnt(2)
	v_mfma_f32_16x16x32_bf16 v[16:19], v[4:7], v[16:19], 0
	s_waitcnt lgkmcnt(1)
	v_mfma_f32_16x16x32_bf16 v[4:7], v[4:7], v[20:23], 0
	ds_read_b128 v[20:23], v161 offset:2368
	ds_read_b128 v[28:31], v161 offset:4672
	s_waitcnt lgkmcnt(1)
	v_mfma_f32_16x16x32_bf16 v[8:11], v[24:27], v[20:23], v[8:11]
	ds_read_b128 v[20:23], v161 offset:6976
	ds_read_b128 v[32:35], v161 offset:9280
	s_waitcnt lgkmcnt(2)
	v_mfma_f32_16x16x32_bf16 v[12:15], v[24:27], v[28:31], v[12:15]
	s_waitcnt vmcnt(19)
	ds_write_b128 v160, v[44:47]
	s_waitcnt vmcnt(18)
	ds_write_b128 v160, v[48:51] offset:1152
	s_waitcnt vmcnt(17)
	ds_write_b128 v160, v[52:55] offset:2304
	s_waitcnt vmcnt(16)
	ds_write_b128 v160, v[56:59] offset:3456
	s_waitcnt vmcnt(15)
	ds_write_b128 v160, v[60:63] offset:4608
	s_waitcnt vmcnt(14)
	ds_write_b128 v160, v[64:67] offset:5760
	s_waitcnt vmcnt(13)
	ds_write_b128 v160, v[68:71] offset:6912
	s_waitcnt vmcnt(12)
	ds_write_b128 v160, v[72:75] offset:8064
	s_waitcnt vmcnt(11)
	ds_write_b128 v160, v[76:79] offset:9216
	s_waitcnt vmcnt(10)
	ds_write_b128 v160, v[80:83] offset:10368
	s_waitcnt lgkmcnt(11)
	v_mfma_f32_16x16x32_bf16 v[16:19], v[24:27], v[20:23], v[16:19]
	ds_read_b128 v[20:23], v2
	s_waitcnt lgkmcnt(11)
	v_mfma_f32_16x16x32_bf16 v[4:7], v[24:27], v[32:35], v[4:7]
	ds_read_b128 v[24:27], v161 offset:2304
	s_waitcnt lgkmcnt(0)
	v_mfma_f32_16x16x32_bf16 v[8:11], v[20:23], v[24:27], v[8:11]
	ds_read_b128 v[24:27], v161 offset:4608
	s_waitcnt lgkmcnt(0)
	v_mfma_f32_16x16x32_bf16 v[12:15], v[20:23], v[24:27], v[12:15]
	ds_read_b128 v[24:27], v161 offset:6912
	ds_read_b128 v[28:31], v161 offset:9216
	ds_read_b128 v[44:47], v2 offset:64
	s_waitcnt lgkmcnt(1)
	v_mfma_f32_16x16x32_bf16 v[48:51], v[20:23], v[28:31], v[4:7]
	s_nop 2
	ds_read_b128 v[4:7], v161 offset:2368
	s_waitcnt lgkmcnt(0)
	v_mfma_f32_16x16x32_bf16 v[52:55], v[44:47], v[4:7], v[8:11]
	ds_read_b128 v[4:7], v161 offset:4672
	v_mfma_f32_16x16x32_bf16 v[16:19], v[20:23], v[24:27], v[16:19]
	s_waitcnt lgkmcnt(0)
	v_mfma_f32_16x16x32_bf16 v[56:59], v[44:47], v[4:7], v[12:15]
	ds_read_b128 v[4:7], v161 offset:6976
	ds_read_b128 v[60:63], v161 offset:9280
	s_waitcnt lgkmcnt(1)
	v_mfma_f32_16x16x32_bf16 v[64:67], v[44:47], v[4:7], v[16:19]
	global_load_dwordx4 v[4:7], v[116:117], off offset:384
	global_load_dwordx4 v[8:11], v[114:115], off offset:384
	global_load_dwordx4 v[12:15], v[112:113], off offset:384
	global_load_dwordx4 v[16:19], v[110:111], off offset:384
	global_load_dwordx4 v[20:23], v[108:109], off offset:384
	global_load_dwordx4 v[36:39], v[158:159], off offset:384
	global_load_dwordx4 v[24:27], v[106:107], off offset:384
	global_load_dwordx4 v[28:31], v[104:105], off offset:384
	global_load_dwordx4 v[32:35], v[102:103], off offset:384
	global_load_dwordx4 v[40:43], v[118:119], off offset:384
	s_waitcnt vmcnt(18)
	ds_write_b128 v160, v[88:91]
	ds_write_b128 v160, v[84:87] offset:1152
	s_waitcnt vmcnt(17)
	ds_write_b128 v160, v[92:95] offset:2304
	s_waitcnt vmcnt(16)
	ds_write_b128 v160, v[96:99] offset:3456
	s_waitcnt vmcnt(15)
	ds_write_b128 v160, v[134:137] offset:4608
	s_waitcnt vmcnt(14)
	ds_write_b128 v160, v[138:141] offset:5760
	s_waitcnt vmcnt(13)
	ds_write_b128 v160, v[142:145] offset:6912
	s_waitcnt vmcnt(12)
	ds_write_b128 v160, v[146:149] offset:8064
	s_waitcnt vmcnt(11)
	ds_write_b128 v160, v[150:153] offset:9216
	s_waitcnt vmcnt(10)
	ds_write_b128 v160, v[154:157] offset:10368
	ds_read_b128 v[68:71], v2
	s_waitcnt lgkmcnt(11)
	v_mfma_f32_16x16x32_bf16 v[44:47], v[44:47], v[60:63], v[48:51]
	s_nop 2
	ds_read_b128 v[48:51], v161 offset:2304
	s_waitcnt lgkmcnt(0)
	v_mfma_f32_16x16x32_bf16 v[48:51], v[68:71], v[48:51], v[52:55]
	s_nop 2
	ds_read_b128 v[52:55], v161 offset:4608
	s_waitcnt lgkmcnt(0)
	v_mfma_f32_16x16x32_bf16 v[52:55], v[68:71], v[52:55], v[56:59]
	s_nop 2
	ds_read_b128 v[56:59], v161 offset:6912
	ds_read_b128 v[60:63], v161 offset:9216
	ds_read_b128 v[88:91], v2 offset:64
	s_waitcnt lgkmcnt(2)
	v_mfma_f32_16x16x32_bf16 v[84:87], v[68:71], v[56:59], v[64:67]
	s_waitcnt lgkmcnt(1)
	v_mfma_f32_16x16x32_bf16 v[92:95], v[68:71], v[60:63], v[44:47]
	s_nop 2
	ds_read_b128 v[44:47], v161 offset:2368
	ds_read_b128 v[56:59], v161 offset:4672
	ds_read_b128 v[134:137], v161 offset:6976
	ds_read_b128 v[138:141], v161 offset:9280
	s_waitcnt lgkmcnt(3)
	v_mfma_f32_16x16x32_bf16 v[96:99], v[88:91], v[44:47], v[48:51]
	s_waitcnt lgkmcnt(2)
	v_mfma_f32_16x16x32_bf16 v[142:145], v[88:91], v[56:59], v[52:55]
	global_load_dwordx4 v[44:47], v[116:117], off offset:512
	global_load_dwordx4 v[48:51], v[114:115], off offset:512
	s_nop 0
	global_load_dwordx4 v[52:55], v[112:113], off offset:512
	global_load_dwordx4 v[56:59], v[110:111], off offset:512
	global_load_dwordx4 v[60:63], v[108:109], off offset:512
	global_load_dwordx4 v[64:67], v[106:107], off offset:512
	global_load_dwordx4 v[68:71], v[104:105], off offset:512
	global_load_dwordx4 v[72:75], v[102:103], off offset:512
	global_load_dwordx4 v[80:83], v[158:159], off offset:512
	global_load_dwordx4 v[76:79], v[118:119], off offset:512
	s_waitcnt vmcnt(19)
	ds_write_b128 v160, v[4:7]
	s_waitcnt vmcnt(14)
	ds_write_b128 v160, v[36:39] offset:1152
	ds_write_b128 v160, v[8:11] offset:2304
	ds_write_b128 v160, v[12:15] offset:3456
	ds_write_b128 v160, v[16:19] offset:4608
	ds_write_b128 v160, v[20:23] offset:5760
	s_waitcnt vmcnt(13)
	ds_write_b128 v160, v[24:27] offset:6912
	s_waitcnt vmcnt(12)
	ds_write_b128 v160, v[28:31] offset:8064
	s_waitcnt vmcnt(11)
	ds_write_b128 v160, v[32:35] offset:9216
	s_waitcnt vmcnt(10)
	ds_write_b128 v160, v[40:43] offset:10368
	s_waitcnt lgkmcnt(11)
	v_mfma_f32_16x16x32_bf16 v[84:87], v[88:91], v[134:137], v[84:87]
	ds_read_b128 v[134:137], v2
	s_waitcnt lgkmcnt(11)
	v_mfma_f32_16x16x32_bf16 v[88:91], v[88:91], v[138:141], v[92:95]
	s_nop 2
	ds_read_b128 v[92:95], v161 offset:2304
	s_waitcnt lgkmcnt(0)
	v_mfma_f32_16x16x32_bf16 v[92:95], v[134:137], v[92:95], v[96:99]
	s_nop 2
	ds_read_b128 v[96:99], v161 offset:4608
	s_waitcnt lgkmcnt(0)
	v_mfma_f32_16x16x32_bf16 v[96:99], v[134:137], v[96:99], v[142:145]
	ds_read_b128 v[138:141], v161 offset:6912
	s_nop 1
	ds_read_b128 v[142:145], v161 offset:9216
	ds_read_b128 v[146:149], v2 offset:64
	s_waitcnt lgkmcnt(2)
	v_mfma_f32_16x16x32_bf16 v[138:141], v[134:137], v[138:141], v[84:87]
	s_nop 2
	ds_read_b128 v[84:87], v161 offset:2368
	s_waitcnt lgkmcnt(2)
	v_mfma_f32_16x16x32_bf16 v[134:137], v[134:137], v[142:145], v[88:91]
	s_nop 2
	ds_read_b128 v[88:91], v161 offset:4672
	s_waitcnt lgkmcnt(1)
	v_mfma_f32_16x16x32_bf16 v[84:87], v[146:149], v[84:87], v[92:95]
	s_nop 2
	ds_read_b128 v[92:95], v161 offset:6976
	ds_read_b128 v[142:145], v161 offset:9280
	s_waitcnt lgkmcnt(2)
	v_mfma_f32_16x16x32_bf16 v[88:91], v[146:149], v[88:91], v[96:99]
	s_waitcnt lgkmcnt(1)
	v_mfma_f32_16x16x32_bf16 v[96:99], v[146:149], v[92:95], v[138:141]
	v_cndmask_b32_e64 v92, 0, 1, s[14:15]
	v_cmp_ne_u32_e64 s[38:39], 1, v92
	s_waitcnt lgkmcnt(0)
	v_mfma_f32_16x16x32_bf16 v[92:95], v[146:149], v[142:145], v[134:137]
	s_cbranch_vccnz .LBB0_196
	v_add_co_u32_e32 v36, vcc, 0xb000, v116
	s_nop 1
	v_addc_co_u32_e32 v37, vcc, 0, v117, vcc
	global_load_dwordx4 v[4:7], v[116:117], off offset:640
	global_load_dwordx4 v[8:11], v[114:115], off offset:640
	global_load_dwordx4 v[12:15], v[112:113], off offset:640
	global_load_dwordx4 v[16:19], v[110:111], off offset:640
	global_load_dwordx4 v[20:23], v[108:109], off offset:640
	global_load_dwordx4 v[24:27], v[106:107], off offset:640
	global_load_dwordx4 v[28:31], v[104:105], off offset:640
	global_load_dwordx4 v[32:35], v[102:103], off offset:640
	s_nop 0
	global_load_dwordx4 v[36:39], v[36:37], off offset:640
	s_nop 0
	global_load_dwordx4 v[40:43], v[118:119], off offset:640
